# P0: the once-read f32 weight loads of the transpose/convert loop also non-temporal (on top of non-temporal x / p loads)
# speedup vs baseline: 1.0351x; 1.0177x over previous
; #define LAS __attribute__((address_space(3)))
; #define LDS_WAIT() asm volatile("s_waitcnt lgkmcnt(0)" ::: "memory")
; #define LDS_WAIT() asm volatile("s_waitcnt lgkmcnt(0)" ::: "memory")
; __device__ __forceinline__ void p0_transpose_item(const float* W, int K, int N, bf16* WT, int k0, int n0, int dst_row0, LAS float* scr, int lane) {
;     const bool ok = (n0 + (lane & 31)) < N;
;     float tv[32];
; #pragma unroll
;     for (int i = 0; i < 32; ++i) { const int kk = 2 * i + (lane >> 5); tv[i] = ok ? W[(size_t)(k0 + kk) * N + n0 + (lane & 31)] : 0.f; }
; #pragma unroll
;     for (int i = 0; i < 32; ++i) { const int kk = 2 * i + (lane >> 5); scr[kk * 33 + (lane & 31)] = tv[i]; }
;     LDS_WAIT(); asm volatile("" ::: "memory");
;     const int c = lane & 7;
; #pragma unroll
;     for (int j = 0; j < 4; ++j) { const int n = (lane >> 3) + 8 * j; const LAS float* s = scr + (8 * c) * 33 + n;
;         v4u o; o.x = pk2(s[0 * 33], s[1 * 33]); o.y = pk2(s[2 * 33], s[3 * 33]); o.z = pk2(s[4 * 33], s[5 * 33]); o.w = pk2(s[6 * 33], s[7 * 33]);
;         *(v4u*)(WT + (size_t)(dst_row0 + n) * K + k0 + 8 * c) = o; }
;     LDS_WAIT(); asm volatile("" ::: "memory");
; }
; __device__ __forceinline__ void p0_prologue(Frame& F, const Args& a) {
;     ...
;     for (int it = F.gw; it < NITEMS; it += F.NGW) {
;         int r = it;
;         if (r < I_IN) { const int kb = r / NB_IN, nb = r % NB_IN; p0_transpose_item(a.in[3], DMODEL, INCOLS, Wt_in, 64 * kb, 32 * nb, win_map(32 * nb), scr, F.lane); continue; } r -= I_IN;
;         if (r < I_SQ) { const int kb = r / 64, nb = r % 64; p0_transpose_item(a.in[21], DMODEL, DMODEL, Wt_out, 64 * kb, 32 * nb, 32 * nb, scr, F.lane); continue; } r -= I_SQ;
;         if (r < I_SQ) { const int kb = r / 64, nb = r % 64; p0_transpose_item(a.in[24], DMODEL, DMODEL, Wt_gate, 64 * kb, 32 * nb, 32 * nb, scr, F.lane); continue; } r -= I_SQ;
;         if (r < I_PLE) { const int kb = r / 64, nb = r % 64; p0_transpose_item(a.in[25], DPLE, DMODEL, Wt_ple, 64 * kb, 32 * nb, 32 * nb, scr, F.lane); continue; } r -= I_PLE;
;         if (r < I_LORA) { p0_transpose_item(a.in[10], 64, RW, W2t, 0, 32 * r, 32 * r, scr, F.lane); continue; } r -= I_LORA;
;         p0_transpose_item(a.in[12], 64, RW, A2t, 0, 32 * r, 32 * r, scr, F.lane);
.LBB0_21:
	s_cmpk_gt_i32 s16, 0x209f
	s_mov_b64 s[2:3], -1
	s_cbranch_scc0 .LBB0_39
	s_cmpk_gt_u32 s16, 0x289f
	s_cbranch_scc0 .LBB0_36
	s_cmpk_gt_u32 s16, 0x309f
	s_cbranch_scc0 .LBB0_33
	s_cmpk_gt_u32 s16, 0x319f
	s_cbranch_scc0 .LBB0_30
	s_cmpk_gt_u32 s16, 0x31bf
	v_add_u32_e32 v92, s10, v5
	s_cbranch_scc0 .LBB0_27
	s_add_i32 s0, s10, 0xfff9c800
	v_lshl_add_u64 v[100:101], s[0:1], 2, v[50:51]
	v_lshl_add_u64 v[102:103], v[100:101], 0, v[2:3]
	v_lshl_add_u64 v[104:105], v[100:101], 0, v[6:7]
	v_lshl_add_u64 v[106:107], v[100:101], 0, v[8:9]
	v_lshl_add_u64 v[108:109], v[100:101], 0, v[10:11]
	v_lshl_add_u64 v[110:111], v[100:101], 0, v[12:13]
	v_lshl_add_u64 v[112:113], v[100:101], 0, v[14:15]
	v_lshl_add_u64 v[114:115], v[100:101], 0, v[16:17]
	v_lshl_add_u64 v[116:117], v[100:101], 0, v[18:19]
	global_load_dword v93, v[102:103], off nt
	global_load_dword v99, v[104:105], off nt
	global_load_dword v118, v[106:107], off nt
	global_load_dword v119, v[108:109], off nt
	global_load_dword v120, v[110:111], off nt
	global_load_dword v121, v[112:113], off nt
	global_load_dword v122, v[114:115], off nt
	global_load_dword v123, v[116:117], off nt
	v_lshl_add_u64 v[102:103], v[100:101], 0, v[20:21]
	v_lshl_add_u64 v[104:105], v[100:101], 0, v[22:23]
	v_lshl_add_u64 v[106:107], v[100:101], 0, v[24:25]
	v_lshl_add_u64 v[108:109], v[100:101], 0, v[26:27]
	v_lshl_add_u64 v[110:111], v[100:101], 0, v[28:29]
	v_lshl_add_u64 v[112:113], v[100:101], 0, v[30:31]
	v_lshl_add_u64 v[114:115], v[100:101], 0, v[32:33]
	v_lshl_add_u64 v[116:117], v[100:101], 0, v[34:35]
	global_load_dword v124, v[102:103], off nt
	global_load_dword v125, v[104:105], off nt
	global_load_dword v126, v[106:107], off nt
	global_load_dword v127, v[108:109], off nt
	global_load_dword v128, v[110:111], off nt
	global_load_dword v129, v[112:113], off nt
	global_load_dword v130, v[114:115], off nt
	global_load_dword v131, v[116:117], off nt
	v_lshl_add_u64 v[102:103], v[100:101], 0, v[36:37]
	v_lshl_add_u64 v[104:105], v[100:101], 0, v[38:39]
	v_lshl_add_u64 v[106:107], v[100:101], 0, v[40:41]
	v_lshl_add_u64 v[108:109], v[100:101], 0, v[42:43]
	v_lshl_add_u64 v[110:111], v[100:101], 0, v[44:45]
	v_lshl_add_u64 v[112:113], v[100:101], 0, v[46:47]
	v_lshl_add_u64 v[114:115], v[100:101], 0, v[48:49]
	v_lshl_add_u64 v[116:117], v[100:101], 0, v[74:75]
	global_load_dword v132, v[102:103], off nt
	global_load_dword v133, v[104:105], off nt
	global_load_dword v134, v[106:107], off nt
	global_load_dword v135, v[108:109], off nt
	global_load_dword v136, v[110:111], off nt
	global_load_dword v137, v[112:113], off nt
	global_load_dword v138, v[114:115], off nt
	s_nop 0
	global_load_dword v116, v[116:117], off nt
	v_lshl_add_u64 v[102:103], v[100:101], 0, v[76:77]
	v_lshl_add_u64 v[104:105], v[100:101], 0, v[78:79]
	v_lshl_add_u64 v[106:107], v[100:101], 0, v[80:81]
	v_lshl_add_u64 v[108:109], v[100:101], 0, v[82:83]
	v_lshl_add_u64 v[110:111], v[100:101], 0, v[84:85]
	v_lshl_add_u64 v[112:113], v[100:101], 0, v[86:87]
	v_lshl_add_u64 v[114:115], v[100:101], 0, v[88:89]
	v_lshl_add_u64 v[100:101], v[100:101], 0, v[90:91]
	global_load_dword v102, v[102:103], off nt
	s_nop 0
	global_load_dword v103, v[104:105], off nt
	s_nop 0
	global_load_dword v104, v[106:107], off nt
	global_load_dword v105, v[108:109], off nt
	s_nop 0
	global_load_dword v106, v[110:111], off nt
	global_load_dword v107, v[112:113], off nt
	global_load_dword v108, v[114:115], off nt
	s_nop 0
	global_load_dword v100, v[100:101], off nt
	v_add_u32_e32 v101, 0x400, v95
	v_add_u32_e32 v109, 0x800, v95
	v_add_u32_e32 v110, 0xc00, v95
	v_add_u32_e32 v111, 0x1000, v95
	v_add_u32_e32 v112, 0x1400, v95
	v_add_u32_e32 v113, 0x1800, v95
	s_mov_b64 s[2:3], 0
	s_waitcnt vmcnt(30)
	ds_write2_b32 v95, v93, v99 offset1:66
	s_waitcnt vmcnt(28)
	ds_write2_b32 v95, v118, v119 offset0:132 offset1:198
	s_waitcnt vmcnt(26)
	ds_write2_b32 v101, v120, v121 offset0:8 offset1:74
	s_waitcnt vmcnt(24)
	ds_write2_b32 v101, v122, v123 offset0:140 offset1:206
	s_waitcnt vmcnt(22)
	ds_write2_b32 v109, v124, v125 offset0:16 offset1:82
	s_waitcnt vmcnt(20)
	ds_write2_b32 v109, v126, v127 offset0:148 offset1:214
	s_waitcnt vmcnt(18)
	ds_write2_b32 v110, v128, v129 offset0:24 offset1:90
	s_waitcnt vmcnt(16)
	ds_write2_b32 v110, v130, v131 offset0:156 offset1:222
	s_waitcnt vmcnt(14)
	ds_write2_b32 v111, v132, v133 offset0:32 offset1:98
	s_waitcnt vmcnt(12)
	ds_write2_b32 v111, v134, v135 offset0:164 offset1:230
	s_waitcnt vmcnt(10)
	ds_write2_b32 v112, v136, v137 offset0:40 offset1:106
	s_waitcnt vmcnt(8)
	ds_write2_b32 v112, v138, v116 offset0:172 offset1:238
	s_waitcnt vmcnt(6)
	ds_write2_b32 v113, v102, v103 offset0:48 offset1:114
	s_waitcnt vmcnt(4)
	ds_write2_b32 v113, v104, v105 offset0:180 offset1:246
	v_add_u32_e32 v93, 0x1c00, v95
	s_waitcnt vmcnt(2)
	ds_write2_b32 v93, v106, v107 offset0:56 offset1:122
	s_waitcnt vmcnt(0)
	ds_write2_b32 v93, v108, v100 offset0:188 offset1:254
	s_waitcnt lgkmcnt(0)
	ds_read2_b32 v[104:105], v94 offset0:33 offset1:41
	ds_read2_b32 v[106:107], v94 offset1:8
	ds_read2_b32 v[108:109], v94 offset0:66 offset1:74
	ds_read2_b32 v[110:111], v94 offset0:99 offset1:107
	ds_read2_b32 v[112:113], v94 offset0:132 offset1:140
	ds_read2_b32 v[114:115], v94 offset0:165 offset1:173
	ds_read2_b32 v[116:117], v94 offset0:198 offset1:206
	ds_read2_b32 v[118:119], v94 offset0:231 offset1:239
	v_add_u32_e32 v120, 0xfff9c800, v92
	v_ashrrev_i32_e32 v121, 31, v120
	v_lshlrev_b64 v[120:121], 7, v[120:121]
	s_waitcnt lgkmcnt(6)
	v_cvt_pk_bf16_f32 v100, v106, v104
	s_waitcnt lgkmcnt(4)
	v_cvt_pk_bf16_f32 v101, v108, v110
	s_waitcnt lgkmcnt(2)
; #define LAS __attribute__((address_space(3)))
; #define LDS_WAIT() asm volatile("s_waitcnt lgkmcnt(0)" ::: "memory")
; #define LDS_WAIT() asm volatile("s_waitcnt lgkmcnt(0)" ::: "memory")
; __device__ __forceinline__ unsigned pk2(float lo, float hi) { f32x2_ v = {lo, hi}; return __builtin_bit_cast(unsigned, __builtin_convertvector(v, bf16x2_)); }
; __device__ __forceinline__ void p0_transpose_item(const float* W, int K, int N, bf16* WT, int k0, int n0, int dst_row0, LAS float* scr, int lane) {
;     const bool ok = (n0 + (lane & 31)) < N;
;     float tv[32];
; #pragma unroll
;     for (int i = 0; i < 32; ++i) { const int kk = 2 * i + (lane >> 5); tv[i] = ok ? W[(size_t)(k0 + kk) * N + n0 + (lane & 31)] : 0.f; }
; #pragma unroll
;     for (int i = 0; i < 32; ++i) { const int kk = 2 * i + (lane >> 5); scr[kk * 33 + (lane & 31)] = tv[i]; }
;     LDS_WAIT(); asm volatile("" ::: "memory");
;     const int c = lane & 7;
; #pragma unroll
;     for (int j = 0; j < 4; ++j) { const int n = (lane >> 3) + 8 * j; const LAS float* s = scr + (8 * c) * 33 + n;
;         v4u o; o.x = pk2(s[0 * 33], s[1 * 33]); o.y = pk2(s[2 * 33], s[3 * 33]); o.z = pk2(s[4 * 33], s[5 * 33]); o.w = pk2(s[6 * 33], s[7 * 33]);
;         *(v4u*)(WT + (size_t)(dst_row0 + n) * K + k0 + 8 * c) = o; }
;     LDS_WAIT(); asm volatile("" ::: "memory");
; }
; __device__ __forceinline__ void p0_prologue(Frame& F, const Args& a) {
;     ...
;         if (r < I_LORA) { p0_transpose_item(a.in[10], 64, RW, W2t, 0, 32 * r, 32 * r, scr, F.lane); continue; } r -= I_LORA;
	v_cvt_pk_bf16_f32 v102, v112, v114
	s_waitcnt lgkmcnt(0)
	v_cvt_pk_bf16_f32 v103, v116, v118
	v_lshl_add_u64 v[120:121], v[52:53], 0, v[120:121]
	v_add_u32_e32 v104, 0xfff9c808, v92
	global_store_dwordx4 v[120:121], v[100:103], off
	s_nop 1
	v_cvt_pk_bf16_f32 v100, v107, v105
	v_ashrrev_i32_e32 v105, 31, v104
	v_cvt_pk_bf16_f32 v101, v109, v111
	v_cvt_pk_bf16_f32 v102, v113, v115
	v_cvt_pk_bf16_f32 v103, v117, v119
	v_lshlrev_b64 v[104:105], 7, v[104:105]
	ds_read2_b32 v[106:107], v94 offset0:49 offset1:57
	ds_read2_b32 v[108:109], v94 offset0:16 offset1:24
	ds_read2_b32 v[110:111], v94 offset0:82 offset1:90
	ds_read2_b32 v[112:113], v94 offset0:115 offset1:123
	ds_read2_b32 v[114:115], v94 offset0:148 offset1:156
	ds_read2_b32 v[116:117], v94 offset0:181 offset1:189
	ds_read2_b32 v[118:119], v94 offset0:214 offset1:222
	ds_read2_b32 v[120:121], v94 offset0:247 offset1:255
	v_lshl_add_u64 v[104:105], v[52:53], 0, v[104:105]
	global_store_dwordx4 v[104:105], v[100:103], off
	v_add_u32_e32 v104, 0xfff9c810, v92
	v_ashrrev_i32_e32 v105, 31, v104
	v_lshlrev_b64 v[104:105], 7, v[104:105]
	s_waitcnt lgkmcnt(6)
	v_cvt_pk_bf16_f32 v100, v108, v106
	s_waitcnt lgkmcnt(4)
	v_cvt_pk_bf16_f32 v101, v110, v112
	s_waitcnt lgkmcnt(2)
	v_cvt_pk_bf16_f32 v102, v114, v116
	s_waitcnt lgkmcnt(0)
	v_cvt_pk_bf16_f32 v103, v118, v120
	v_lshl_add_u64 v[104:105], v[52:53], 0, v[104:105]
	global_store_dwordx4 v[104:105], v[100:103], off
	v_add_u32_e32 v104, 0xfff9c818, v92
	v_ashrrev_i32_e32 v105, 31, v104
	v_lshlrev_b64 v[104:105], 7, v[104:105]
	v_cvt_pk_bf16_f32 v100, v109, v107
	v_cvt_pk_bf16_f32 v101, v111, v113
	v_cvt_pk_bf16_f32 v102, v115, v117
	v_cvt_pk_bf16_f32 v103, v119, v121
	v_lshl_add_u64 v[104:105], v[52:53], 0, v[104:105]
	global_store_dwordx4 v[104:105], v[100:103], off
	s_waitcnt lgkmcnt(0)
.LBB0_27:
	s_andn2_b64 vcc, exec, s[2:3]
	s_cbranch_vccnz .LBB0_29
	s_add_i32 s0, s10, 0xfff9cc00
	v_lshl_add_u64 v[100:101], s[0:1], 2, v[54:55]
	v_lshl_add_u64 v[102:103], v[100:101], 0, v[2:3]
	v_lshl_add_u64 v[104:105], v[100:101], 0, v[6:7]
	v_lshl_add_u64 v[106:107], v[100:101], 0, v[8:9]
	v_lshl_add_u64 v[108:109], v[100:101], 0, v[10:11]
	v_lshl_add_u64 v[110:111], v[100:101], 0, v[12:13]
	v_lshl_add_u64 v[112:113], v[100:101], 0, v[14:15]
	v_lshl_add_u64 v[114:115], v[100:101], 0, v[16:17]
	v_lshl_add_u64 v[116:117], v[100:101], 0, v[18:19]
	global_load_dword v93, v[102:103], off nt
	global_load_dword v99, v[104:105], off nt
	global_load_dword v118, v[106:107], off nt
	global_load_dword v119, v[108:109], off nt
	global_load_dword v120, v[110:111], off nt
	global_load_dword v121, v[112:113], off nt
	global_load_dword v122, v[114:115], off nt
	global_load_dword v123, v[116:117], off nt
	v_lshl_add_u64 v[102:103], v[100:101], 0, v[20:21]
	v_lshl_add_u64 v[104:105], v[100:101], 0, v[22:23]
	v_lshl_add_u64 v[106:107], v[100:101], 0, v[24:25]
	v_lshl_add_u64 v[108:109], v[100:101], 0, v[26:27]
	v_lshl_add_u64 v[110:111], v[100:101], 0, v[28:29]
	v_lshl_add_u64 v[112:113], v[100:101], 0, v[30:31]
	v_lshl_add_u64 v[114:115], v[100:101], 0, v[32:33]
	v_lshl_add_u64 v[116:117], v[100:101], 0, v[34:35]
	global_load_dword v124, v[102:103], off nt
	global_load_dword v125, v[104:105], off nt
	global_load_dword v126, v[106:107], off nt
	global_load_dword v127, v[108:109], off nt
	global_load_dword v128, v[110:111], off nt
	global_load_dword v129, v[112:113], off nt
	global_load_dword v130, v[114:115], off nt
	global_load_dword v131, v[116:117], off nt
	v_lshl_add_u64 v[102:103], v[100:101], 0, v[36:37]
	v_lshl_add_u64 v[104:105], v[100:101], 0, v[38:39]
	v_lshl_add_u64 v[106:107], v[100:101], 0, v[40:41]
	v_lshl_add_u64 v[108:109], v[100:101], 0, v[42:43]
	v_lshl_add_u64 v[110:111], v[100:101], 0, v[44:45]
	v_lshl_add_u64 v[112:113], v[100:101], 0, v[46:47]
	v_lshl_add_u64 v[114:115], v[100:101], 0, v[48:49]
	v_lshl_add_u64 v[116:117], v[100:101], 0, v[74:75]
	global_load_dword v132, v[102:103], off nt
	global_load_dword v133, v[104:105], off nt
	global_load_dword v134, v[106:107], off nt
	global_load_dword v135, v[108:109], off nt
	global_load_dword v136, v[110:111], off nt
	global_load_dword v137, v[112:113], off nt
	global_load_dword v138, v[114:115], off nt
	s_nop 0
	global_load_dword v116, v[116:117], off nt
	v_lshl_add_u64 v[102:103], v[100:101], 0, v[76:77]
	v_lshl_add_u64 v[104:105], v[100:101], 0, v[78:79]
	v_lshl_add_u64 v[106:107], v[100:101], 0, v[80:81]
	v_lshl_add_u64 v[108:109], v[100:101], 0, v[82:83]
	v_lshl_add_u64 v[110:111], v[100:101], 0, v[84:85]
	v_lshl_add_u64 v[112:113], v[100:101], 0, v[86:87]
	v_lshl_add_u64 v[114:115], v[100:101], 0, v[88:89]
	v_lshl_add_u64 v[100:101], v[100:101], 0, v[90:91]
	global_load_dword v102, v[102:103], off nt
	s_nop 0
	global_load_dword v103, v[104:105], off nt
	s_nop 0
	global_load_dword v104, v[106:107], off nt
	global_load_dword v105, v[108:109], off nt
	s_nop 0
	global_load_dword v106, v[110:111], off nt
	global_load_dword v107, v[112:113], off nt
	global_load_dword v108, v[114:115], off nt
	s_nop 0
	global_load_dword v100, v[100:101], off nt
	v_add_u32_e32 v101, 0x400, v95
	v_add_u32_e32 v109, 0x800, v95
	v_add_u32_e32 v110, 0xc00, v95
	v_add_u32_e32 v111, 0x1000, v95
	v_add_u32_e32 v112, 0x1400, v95
	v_add_u32_e32 v113, 0x1800, v95
	s_waitcnt vmcnt(30)
; #define LAS __attribute__((address_space(3)))
; #define LDS_WAIT() asm volatile("s_waitcnt lgkmcnt(0)" ::: "memory")
; #define LDS_WAIT() asm volatile("s_waitcnt lgkmcnt(0)" ::: "memory")
; __device__ __forceinline__ unsigned pk2(float lo, float hi) { f32x2_ v = {lo, hi}; return __builtin_bit_cast(unsigned, __builtin_convertvector(v, bf16x2_)); }
; __device__ __forceinline__ void p0_transpose_item(const float* W, int K, int N, bf16* WT, int k0, int n0, int dst_row0, LAS float* scr, int lane) {
;     ...
;     for (int i = 0; i < 32; ++i) { const int kk = 2 * i + (lane >> 5); scr[kk * 33 + (lane & 31)] = tv[i]; }
;     LDS_WAIT(); asm volatile("" ::: "memory");
;     const int c = lane & 7;
; #pragma unroll
;     for (int j = 0; j < 4; ++j) { const int n = (lane >> 3) + 8 * j; const LAS float* s = scr + (8 * c) * 33 + n;
;         v4u o; o.x = pk2(s[0 * 33], s[1 * 33]); o.y = pk2(s[2 * 33], s[3 * 33]); o.z = pk2(s[4 * 33], s[5 * 33]); o.w = pk2(s[6 * 33], s[7 * 33]);
;         *(v4u*)(WT + (size_t)(dst_row0 + n) * K + k0 + 8 * c) = o; }
;     LDS_WAIT(); asm volatile("" ::: "memory");
; }
	ds_write2_b32 v95, v93, v99 offset1:66
	s_waitcnt vmcnt(28)
	ds_write2_b32 v95, v118, v119 offset0:132 offset1:198
	s_waitcnt vmcnt(26)
	ds_write2_b32 v101, v120, v121 offset0:8 offset1:74
	s_waitcnt vmcnt(24)
	ds_write2_b32 v101, v122, v123 offset0:140 offset1:206
	s_waitcnt vmcnt(22)
	ds_write2_b32 v109, v124, v125 offset0:16 offset1:82
	s_waitcnt vmcnt(20)
	ds_write2_b32 v109, v126, v127 offset0:148 offset1:214
	s_waitcnt vmcnt(18)
	ds_write2_b32 v110, v128, v129 offset0:24 offset1:90
	s_waitcnt vmcnt(16)
	ds_write2_b32 v110, v130, v131 offset0:156 offset1:222
	s_waitcnt vmcnt(14)
	ds_write2_b32 v111, v132, v133 offset0:32 offset1:98
	s_waitcnt vmcnt(12)
	ds_write2_b32 v111, v134, v135 offset0:164 offset1:230
	s_waitcnt vmcnt(10)
	ds_write2_b32 v112, v136, v137 offset0:40 offset1:106
	s_waitcnt vmcnt(8)
	ds_write2_b32 v112, v138, v116 offset0:172 offset1:238
	s_waitcnt vmcnt(6)
	ds_write2_b32 v113, v102, v103 offset0:48 offset1:114
	s_waitcnt vmcnt(4)
	ds_write2_b32 v113, v104, v105 offset0:180 offset1:246
	v_add_u32_e32 v93, 0x1c00, v95
	s_waitcnt vmcnt(2)
	ds_write2_b32 v93, v106, v107 offset0:56 offset1:122
	s_waitcnt vmcnt(0)
	ds_write2_b32 v93, v108, v100 offset0:188 offset1:254
	s_waitcnt lgkmcnt(0)
	ds_read2_b32 v[104:105], v94 offset0:33 offset1:41
	ds_read2_b32 v[106:107], v94 offset1:8
	ds_read2_b32 v[108:109], v94 offset0:66 offset1:74
	ds_read2_b32 v[110:111], v94 offset0:99 offset1:107
	ds_read2_b32 v[112:113], v94 offset0:132 offset1:140
	ds_read2_b32 v[114:115], v94 offset0:165 offset1:173
	ds_read2_b32 v[116:117], v94 offset0:198 offset1:206
	ds_read2_b32 v[118:119], v94 offset0:231 offset1:239
	v_add_u32_e32 v120, 0xfff9cc00, v92
	v_ashrrev_i32_e32 v121, 31, v120
	v_lshlrev_b64 v[120:121], 7, v[120:121]
	s_waitcnt lgkmcnt(6)
	v_cvt_pk_bf16_f32 v100, v106, v104
	s_waitcnt lgkmcnt(4)
	v_cvt_pk_bf16_f32 v101, v108, v110
	s_waitcnt lgkmcnt(2)
	v_cvt_pk_bf16_f32 v102, v112, v114
	s_waitcnt lgkmcnt(0)
	v_cvt_pk_bf16_f32 v103, v116, v118
	v_lshl_add_u64 v[120:121], v[56:57], 0, v[120:121]
	v_add_u32_e32 v104, 0xfff9cc08, v92
	global_store_dwordx4 v[120:121], v[100:103], off
	s_nop 1
	v_cvt_pk_bf16_f32 v100, v107, v105
	v_ashrrev_i32_e32 v105, 31, v104
	v_cvt_pk_bf16_f32 v101, v109, v111
	v_cvt_pk_bf16_f32 v102, v113, v115
	v_cvt_pk_bf16_f32 v103, v117, v119
	v_lshlrev_b64 v[104:105], 7, v[104:105]
	ds_read2_b32 v[106:107], v94 offset0:49 offset1:57
	ds_read2_b32 v[108:109], v94 offset0:16 offset1:24
	ds_read2_b32 v[110:111], v94 offset0:82 offset1:90
	ds_read2_b32 v[112:113], v94 offset0:115 offset1:123
	ds_read2_b32 v[114:115], v94 offset0:148 offset1:156
	ds_read2_b32 v[116:117], v94 offset0:181 offset1:189
	ds_read2_b32 v[118:119], v94 offset0:214 offset1:222
	ds_read2_b32 v[120:121], v94 offset0:247 offset1:255
	v_lshl_add_u64 v[104:105], v[56:57], 0, v[104:105]
	global_store_dwordx4 v[104:105], v[100:103], off
	v_add_u32_e32 v104, 0xfff9cc10, v92
	v_ashrrev_i32_e32 v105, 31, v104
	v_add_u32_e32 v92, 0xfff9cc18, v92
	v_lshlrev_b64 v[104:105], 7, v[104:105]
	v_ashrrev_i32_e32 v93, 31, v92
	s_waitcnt lgkmcnt(6)
	v_cvt_pk_bf16_f32 v100, v108, v106
	s_waitcnt lgkmcnt(4)
	v_cvt_pk_bf16_f32 v101, v110, v112
	s_waitcnt lgkmcnt(2)
	v_cvt_pk_bf16_f32 v102, v114, v116
	s_waitcnt lgkmcnt(0)
	v_cvt_pk_bf16_f32 v103, v118, v120
	v_lshl_add_u64 v[104:105], v[56:57], 0, v[104:105]
	v_lshlrev_b64 v[92:93], 7, v[92:93]
	global_store_dwordx4 v[104:105], v[100:103], off
	v_lshl_add_u64 v[92:93], v[56:57], 0, v[92:93]
	s_nop 0
	v_cvt_pk_bf16_f32 v100, v109, v107
	v_cvt_pk_bf16_f32 v101, v111, v113
	v_cvt_pk_bf16_f32 v102, v115, v117
	v_cvt_pk_bf16_f32 v103, v119, v121
	global_store_dwordx4 v[92:93], v[100:103], off
	s_waitcnt lgkmcnt(0)

; #define LAS __attribute__((address_space(3)))
; __device__ __forceinline__ void p0_transpose_item(const float* W, int K, int N, bf16* WT, int k0, int n0, int dst_row0, LAS float* scr, int lane) {
;     const bool ok = (n0 + (lane & 31)) < N;
;     float tv[32];
; #pragma unroll
;     for (int i = 0; i < 32; ++i) { const int kk = 2 * i + (lane >> 5); tv[i] = ok ? W[(size_t)(k0 + kk) * N + n0 + (lane & 31)] : 0.f; }
; #pragma unroll
;     for (int i = 0; i < 32; ++i) { const int kk = 2 * i + (lane >> 5); scr[kk * 33 + (lane & 31)] = tv[i]; }
; __device__ __forceinline__ void p0_prologue(Frame& F, const Args& a) {
;     ...
;         if (r < I_PLE) { const int kb = r / 64, nb = r % 64; p0_transpose_item(a.in[25], DPLE, DMODEL, Wt_ple, 64 * kb, 32 * nb, 32 * nb, scr, F.lane); continue; } r -= I_PLE;
.LBB0_30:
	s_andn2_b64 vcc, exec, s[2:3]
	s_cbranch_vccnz .LBB0_32
	s_add_i32 s0, s16, 0xffffcf60
	s_and_b32 s2, s0, 0xffffffc0
	s_add_i32 s0, s10, 0xfff9ec00
	s_and_b32 s4, s0, 0x7e0
	v_add_u32_e32 v92, s2, v0
	s_lshl_b32 s0, s4, 2
	v_ashrrev_i32_e32 v93, 31, v92
	v_lshl_add_u64 v[100:101], v[58:59], 0, s[0:1]
	v_lshlrev_b64 v[92:93], 13, v[92:93]
	v_lshl_add_u64 v[92:93], v[100:101], 0, v[92:93]
	v_add_co_u32_e32 v100, vcc, 0x4000, v92
	s_mov_b32 s3, s1
	s_nop 0
	v_addc_co_u32_e32 v101, vcc, 0, v93, vcc
	v_add_co_u32_e32 v102, vcc, 0x8000, v92
	s_nop 1
	v_addc_co_u32_e32 v103, vcc, 0, v93, vcc
	v_add_co_u32_e32 v104, vcc, 0xc000, v92
	s_nop 1
	v_addc_co_u32_e32 v105, vcc, 0, v93, vcc
	v_add_co_u32_e32 v106, vcc, 0x10000, v92
	s_nop 1
	v_addc_co_u32_e32 v107, vcc, 0, v93, vcc
	v_add_co_u32_e32 v108, vcc, 0x14000, v92
	s_nop 1
	v_addc_co_u32_e32 v109, vcc, 0, v93, vcc
	v_add_co_u32_e32 v110, vcc, 0x18000, v92
	s_nop 1
	v_addc_co_u32_e32 v111, vcc, 0, v93, vcc
	v_add_co_u32_e32 v112, vcc, 0x1c000, v92
	s_nop 1
	v_addc_co_u32_e32 v113, vcc, 0, v93, vcc
	global_load_dword v99, v[92:93], off nt
	global_load_dword v116, v[100:101], off nt
	global_load_dword v117, v[102:103], off nt
	global_load_dword v118, v[104:105], off nt
	global_load_dword v119, v[106:107], off nt
	global_load_dword v120, v[108:109], off nt
	global_load_dword v121, v[110:111], off nt
	global_load_dword v122, v[112:113], off nt
	v_add_co_u32_e32 v100, vcc, 0x20000, v92
	s_nop 1
	v_addc_co_u32_e32 v101, vcc, 0, v93, vcc
	v_add_co_u32_e32 v102, vcc, 0x24000, v92
	s_nop 1
	v_addc_co_u32_e32 v103, vcc, 0, v93, vcc
	v_add_co_u32_e32 v104, vcc, 0x28000, v92
	s_nop 1
	v_addc_co_u32_e32 v105, vcc, 0, v93, vcc
	v_add_co_u32_e32 v106, vcc, 0x2c000, v92
	s_nop 1
	v_addc_co_u32_e32 v107, vcc, 0, v93, vcc
	v_add_co_u32_e32 v108, vcc, 0x30000, v92
	s_nop 1
	v_addc_co_u32_e32 v109, vcc, 0, v93, vcc
	v_add_co_u32_e32 v110, vcc, 0x34000, v92
	s_nop 1
	v_addc_co_u32_e32 v111, vcc, 0, v93, vcc
	v_add_co_u32_e32 v112, vcc, 0x38000, v92
	s_nop 1
	v_addc_co_u32_e32 v113, vcc, 0, v93, vcc
	v_add_co_u32_e32 v114, vcc, 0x3c000, v92
	s_nop 1
	v_addc_co_u32_e32 v115, vcc, 0, v93, vcc
	global_load_dword v123, v[100:101], off nt
	global_load_dword v124, v[102:103], off nt
	global_load_dword v125, v[104:105], off nt
	global_load_dword v126, v[106:107], off nt
	global_load_dword v127, v[108:109], off nt
	global_load_dword v128, v[110:111], off nt
	global_load_dword v129, v[112:113], off nt
	global_load_dword v130, v[114:115], off nt
	v_add_co_u32_e32 v100, vcc, 0x40000, v92
	s_nop 1
	v_addc_co_u32_e32 v101, vcc, 0, v93, vcc
	v_add_co_u32_e32 v102, vcc, 0x44000, v92
	s_nop 1
	v_addc_co_u32_e32 v103, vcc, 0, v93, vcc
	v_add_co_u32_e32 v104, vcc, 0x48000, v92
	s_nop 1
	v_addc_co_u32_e32 v105, vcc, 0, v93, vcc
	v_add_co_u32_e32 v106, vcc, 0x4c000, v92
	s_nop 1
	v_addc_co_u32_e32 v107, vcc, 0, v93, vcc
	v_add_co_u32_e32 v108, vcc, 0x50000, v92
	s_nop 1
	v_addc_co_u32_e32 v109, vcc, 0, v93, vcc
	v_add_co_u32_e32 v110, vcc, 0x54000, v92
	s_nop 1
	v_addc_co_u32_e32 v111, vcc, 0, v93, vcc
	v_add_co_u32_e32 v112, vcc, 0x58000, v92
	s_nop 1
	v_addc_co_u32_e32 v113, vcc, 0, v93, vcc
	v_add_co_u32_e32 v114, vcc, 0x5c000, v92
	s_nop 1
	v_addc_co_u32_e32 v115, vcc, 0, v93, vcc
	global_load_dword v131, v[100:101], off nt
	global_load_dword v132, v[102:103], off nt
	global_load_dword v133, v[104:105], off nt
	global_load_dword v134, v[106:107], off nt
	global_load_dword v135, v[108:109], off nt
	global_load_dword v136, v[110:111], off nt
	global_load_dword v137, v[112:113], off nt
	s_nop 0
	global_load_dword v114, v[114:115], off nt
	v_add_co_u32_e32 v100, vcc, 0x60000, v92
	s_nop 1
	v_addc_co_u32_e32 v101, vcc, 0, v93, vcc
	v_add_co_u32_e32 v102, vcc, 0x64000, v92
	s_nop 1
	v_addc_co_u32_e32 v103, vcc, 0, v93, vcc
	v_add_co_u32_e32 v104, vcc, 0x68000, v92
	s_nop 1
	v_addc_co_u32_e32 v105, vcc, 0, v93, vcc
	v_add_co_u32_e32 v106, vcc, 0x6c000, v92
	s_nop 1
	v_addc_co_u32_e32 v107, vcc, 0, v93, vcc
	v_add_co_u32_e32 v108, vcc, 0x70000, v92
	s_nop 1
	v_addc_co_u32_e32 v109, vcc, 0, v93, vcc
	v_add_co_u32_e32 v110, vcc, 0x74000, v92
	s_nop 1
	v_addc_co_u32_e32 v111, vcc, 0, v93, vcc
	v_add_co_u32_e32 v112, vcc, 0x78000, v92
	s_nop 1
	v_addc_co_u32_e32 v113, vcc, 0, v93, vcc
	v_add_co_u32_e32 v92, vcc, 0x7c000, v92
	s_nop 1
	v_addc_co_u32_e32 v93, vcc, 0, v93, vcc
	global_load_dword v100, v[100:101], off nt
	s_nop 0
	global_load_dword v101, v[102:103], off nt
	s_nop 0
	global_load_dword v102, v[104:105], off nt
	global_load_dword v103, v[106:107], off nt
	s_nop 0
	global_load_dword v104, v[108:109], off nt
	global_load_dword v105, v[110:111], off nt
	global_load_dword v106, v[112:113], off nt
	s_nop 0
	global_load_dword v92, v[92:93], off nt
	v_add_u32_e32 v93, 0x400, v95
	s_waitcnt vmcnt(30)
; #define LAS __attribute__((address_space(3)))
; #define LDS_WAIT() asm volatile("s_waitcnt lgkmcnt(0)" ::: "memory")
; #define LDS_WAIT() asm volatile("s_waitcnt lgkmcnt(0)" ::: "memory")
; __device__ __forceinline__ unsigned pk2(float lo, float hi) { f32x2_ v = {lo, hi}; return __builtin_bit_cast(unsigned, __builtin_convertvector(v, bf16x2_)); }
; __device__ __forceinline__ void p0_transpose_item(const float* W, int K, int N, bf16* WT, int k0, int n0, int dst_row0, LAS float* scr, int lane) {
;     ...
;     for (int i = 0; i < 32; ++i) { const int kk = 2 * i + (lane >> 5); scr[kk * 33 + (lane & 31)] = tv[i]; }
;     LDS_WAIT(); asm volatile("" ::: "memory");
;     const int c = lane & 7;
; #pragma unroll
;     for (int j = 0; j < 4; ++j) { const int n = (lane >> 3) + 8 * j; const LAS float* s = scr + (8 * c) * 33 + n;
;         v4u o; o.x = pk2(s[0 * 33], s[1 * 33]); o.y = pk2(s[2 * 33], s[3 * 33]); o.z = pk2(s[4 * 33], s[5 * 33]); o.w = pk2(s[6 * 33], s[7 * 33]);
;         *(v4u*)(WT + (size_t)(dst_row0 + n) * K + k0 + 8 * c) = o; }
;     LDS_WAIT(); asm volatile("" ::: "memory");
; }
	ds_write2_b32 v95, v99, v116 offset1:66
	s_waitcnt vmcnt(28)
	ds_write2_b32 v95, v117, v118 offset0:132 offset1:198
	s_waitcnt vmcnt(26)
	ds_write2_b32 v93, v119, v120 offset0:8 offset1:74
	s_waitcnt vmcnt(24)
	ds_write2_b32 v93, v121, v122 offset0:140 offset1:206
	v_add_u32_e32 v93, 0x800, v95
	s_waitcnt vmcnt(22)
	ds_write2_b32 v93, v123, v124 offset0:16 offset1:82
	s_waitcnt vmcnt(20)
	ds_write2_b32 v93, v125, v126 offset0:148 offset1:214
	v_add_u32_e32 v93, 0xc00, v95
	s_waitcnt vmcnt(18)
	ds_write2_b32 v93, v127, v128 offset0:24 offset1:90
	s_waitcnt vmcnt(16)
	ds_write2_b32 v93, v129, v130 offset0:156 offset1:222
	v_add_u32_e32 v93, 0x1000, v95
	s_waitcnt vmcnt(14)
	ds_write2_b32 v93, v131, v132 offset0:32 offset1:98
	s_waitcnt vmcnt(12)
	ds_write2_b32 v93, v133, v134 offset0:164 offset1:230
	v_add_u32_e32 v93, 0x1400, v95
	s_waitcnt vmcnt(10)
	ds_write2_b32 v93, v135, v136 offset0:40 offset1:106
	s_waitcnt vmcnt(8)
	ds_write2_b32 v93, v137, v114 offset0:172 offset1:238
	v_add_u32_e32 v93, 0x1800, v95
	s_waitcnt vmcnt(6)
	ds_write2_b32 v93, v100, v101 offset0:48 offset1:114
	s_waitcnt vmcnt(4)
	ds_write2_b32 v93, v102, v103 offset0:180 offset1:246
	v_add_u32_e32 v93, 0x1c00, v95
	s_waitcnt vmcnt(2)
	ds_write2_b32 v93, v104, v105 offset0:56 offset1:122
	s_waitcnt vmcnt(0)
	ds_write2_b32 v93, v106, v92 offset0:188 offset1:254
	s_waitcnt lgkmcnt(0)
	ds_read2_b32 v[92:93], v94 offset0:33 offset1:41
	ds_read2_b32 v[104:105], v94 offset1:8
	ds_read2_b32 v[106:107], v94 offset0:66 offset1:74
	ds_read2_b32 v[108:109], v94 offset0:99 offset1:107
	ds_read2_b32 v[110:111], v94 offset0:132 offset1:140
	ds_read2_b32 v[112:113], v94 offset0:165 offset1:173
	ds_read2_b32 v[114:115], v94 offset0:198 offset1:206
	ds_read2_b32 v[116:117], v94 offset0:231 offset1:239
	v_add_u32_e32 v120, s4, v5
	v_ashrrev_i32_e32 v121, 31, v120
	v_lshl_add_u64 v[118:119], s[2:3], 1, v[60:61]
	v_lshlrev_b64 v[120:121], 9, v[120:121]
	s_waitcnt lgkmcnt(6)
	v_cvt_pk_bf16_f32 v100, v104, v92
	s_waitcnt lgkmcnt(4)
	v_cvt_pk_bf16_f32 v101, v106, v108
	s_waitcnt lgkmcnt(2)
	v_cvt_pk_bf16_f32 v102, v110, v112
	s_waitcnt lgkmcnt(0)
	v_cvt_pk_bf16_f32 v103, v114, v116
	v_lshl_add_u64 v[120:121], v[118:119], 0, v[120:121]
	v_add_u32_e32 v92, s4, v96
	global_store_dwordx4 v[120:121], v[100:103], off
	s_nop 1
	v_cvt_pk_bf16_f32 v100, v105, v93
	v_ashrrev_i32_e32 v93, 31, v92
	v_cvt_pk_bf16_f32 v101, v107, v109
	v_cvt_pk_bf16_f32 v102, v111, v113
	v_cvt_pk_bf16_f32 v103, v115, v117
	v_lshlrev_b64 v[92:93], 9, v[92:93]
	ds_read2_b32 v[104:105], v94 offset0:49 offset1:57
	ds_read2_b32 v[106:107], v94 offset0:16 offset1:24
	ds_read2_b32 v[108:109], v94 offset0:82 offset1:90
	ds_read2_b32 v[110:111], v94 offset0:115 offset1:123
	ds_read2_b32 v[112:113], v94 offset0:148 offset1:156
	ds_read2_b32 v[114:115], v94 offset0:181 offset1:189
	ds_read2_b32 v[116:117], v94 offset0:214 offset1:222
	ds_read2_b32 v[120:121], v94 offset0:247 offset1:255
	v_lshl_add_u64 v[92:93], v[118:119], 0, v[92:93]
	global_store_dwordx4 v[92:93], v[100:103], off
	v_add_u32_e32 v92, s4, v97
	v_ashrrev_i32_e32 v93, 31, v92
	v_lshlrev_b64 v[92:93], 9, v[92:93]
	s_waitcnt lgkmcnt(6)
	v_cvt_pk_bf16_f32 v100, v106, v104
	s_waitcnt lgkmcnt(4)
	v_cvt_pk_bf16_f32 v101, v108, v110
	s_waitcnt lgkmcnt(2)
	v_cvt_pk_bf16_f32 v102, v112, v114
	s_waitcnt lgkmcnt(0)
	v_cvt_pk_bf16_f32 v103, v116, v120
	v_lshl_add_u64 v[92:93], v[118:119], 0, v[92:93]
	global_store_dwordx4 v[92:93], v[100:103], off
	v_add_u32_e32 v92, s4, v98
	v_ashrrev_i32_e32 v93, 31, v92
	v_lshlrev_b64 v[92:93], 9, v[92:93]
	v_cvt_pk_bf16_f32 v100, v107, v105
	v_cvt_pk_bf16_f32 v101, v109, v111
	v_cvt_pk_bf16_f32 v102, v113, v115
	v_cvt_pk_bf16_f32 v103, v117, v121
	v_lshl_add_u64 v[92:93], v[118:119], 0, v[92:93]
	global_store_dwordx4 v[92:93], v[100:103], off
	s_waitcnt lgkmcnt(0)

; #define LAS __attribute__((address_space(3)))
; __device__ __forceinline__ void p0_transpose_item(const float* W, int K, int N, bf16* WT, int k0, int n0, int dst_row0, LAS float* scr, int lane) {
;     const bool ok = (n0 + (lane & 31)) < N;
;     float tv[32];
; #pragma unroll
;     for (int i = 0; i < 32; ++i) { const int kk = 2 * i + (lane >> 5); tv[i] = ok ? W[(size_t)(k0 + kk) * N + n0 + (lane & 31)] : 0.f; }
; #pragma unroll
;     for (int i = 0; i < 32; ++i) { const int kk = 2 * i + (lane >> 5); scr[kk * 33 + (lane & 31)] = tv[i]; }
; __device__ __forceinline__ void p0_prologue(Frame& F, const Args& a) {
;     ...
;         if (r < I_SQ) { const int kb = r / 64, nb = r % 64; p0_transpose_item(a.in[24], DMODEL, DMODEL, Wt_gate, 64 * kb, 32 * nb, 32 * nb, scr, F.lane); continue; } r -= I_SQ;
.LBB0_33:
	s_andn2_b64 vcc, exec, s[2:3]
	s_cbranch_vccnz .LBB0_35
	s_add_i32 s0, s16, 0xffffd760
	s_and_b32 s2, s0, 0xffffffc0
	s_add_i32 s0, s10, 0xfffaec00
	s_and_b32 s4, s0, 0x7e0
	v_add_u32_e32 v92, s2, v0
	s_lshl_b32 s0, s4, 2
	v_ashrrev_i32_e32 v93, 31, v92
	v_lshl_add_u64 v[100:101], v[62:63], 0, s[0:1]
	v_lshlrev_b64 v[92:93], 13, v[92:93]
	v_lshl_add_u64 v[92:93], v[100:101], 0, v[92:93]
	v_add_co_u32_e32 v100, vcc, 0x4000, v92
	s_mov_b32 s3, s1
	s_nop 0
	v_addc_co_u32_e32 v101, vcc, 0, v93, vcc
	v_add_co_u32_e32 v102, vcc, 0x8000, v92
	s_nop 1
	v_addc_co_u32_e32 v103, vcc, 0, v93, vcc
	v_add_co_u32_e32 v104, vcc, 0xc000, v92
	s_nop 1
	v_addc_co_u32_e32 v105, vcc, 0, v93, vcc
	v_add_co_u32_e32 v106, vcc, 0x10000, v92
	s_nop 1
	v_addc_co_u32_e32 v107, vcc, 0, v93, vcc
	v_add_co_u32_e32 v108, vcc, 0x14000, v92
	s_nop 1
	v_addc_co_u32_e32 v109, vcc, 0, v93, vcc
	v_add_co_u32_e32 v110, vcc, 0x18000, v92
	s_nop 1
	v_addc_co_u32_e32 v111, vcc, 0, v93, vcc
	v_add_co_u32_e32 v112, vcc, 0x1c000, v92
	s_nop 1
	v_addc_co_u32_e32 v113, vcc, 0, v93, vcc
	global_load_dword v99, v[92:93], off nt
	global_load_dword v116, v[100:101], off nt
	global_load_dword v117, v[102:103], off nt
	global_load_dword v118, v[104:105], off nt
	global_load_dword v119, v[106:107], off nt
	global_load_dword v120, v[108:109], off nt
	global_load_dword v121, v[110:111], off nt
	global_load_dword v122, v[112:113], off nt
	v_add_co_u32_e32 v100, vcc, 0x20000, v92
	s_nop 1
	v_addc_co_u32_e32 v101, vcc, 0, v93, vcc
	v_add_co_u32_e32 v102, vcc, 0x24000, v92
	s_nop 1
	v_addc_co_u32_e32 v103, vcc, 0, v93, vcc
	v_add_co_u32_e32 v104, vcc, 0x28000, v92
	s_nop 1
	v_addc_co_u32_e32 v105, vcc, 0, v93, vcc
	v_add_co_u32_e32 v106, vcc, 0x2c000, v92
	s_nop 1
	v_addc_co_u32_e32 v107, vcc, 0, v93, vcc
	v_add_co_u32_e32 v108, vcc, 0x30000, v92
	s_nop 1
	v_addc_co_u32_e32 v109, vcc, 0, v93, vcc
	v_add_co_u32_e32 v110, vcc, 0x34000, v92
	s_nop 1
	v_addc_co_u32_e32 v111, vcc, 0, v93, vcc
	v_add_co_u32_e32 v112, vcc, 0x38000, v92
	s_nop 1
	v_addc_co_u32_e32 v113, vcc, 0, v93, vcc
	v_add_co_u32_e32 v114, vcc, 0x3c000, v92
	s_nop 1
	v_addc_co_u32_e32 v115, vcc, 0, v93, vcc
	global_load_dword v123, v[100:101], off nt
	global_load_dword v124, v[102:103], off nt
	global_load_dword v125, v[104:105], off nt
	global_load_dword v126, v[106:107], off nt
	global_load_dword v127, v[108:109], off nt
	global_load_dword v128, v[110:111], off nt
	global_load_dword v129, v[112:113], off nt
	global_load_dword v130, v[114:115], off nt
	v_add_co_u32_e32 v100, vcc, 0x40000, v92
	s_nop 1
	v_addc_co_u32_e32 v101, vcc, 0, v93, vcc
	v_add_co_u32_e32 v102, vcc, 0x44000, v92
	s_nop 1
	v_addc_co_u32_e32 v103, vcc, 0, v93, vcc
	v_add_co_u32_e32 v104, vcc, 0x48000, v92
	s_nop 1
	v_addc_co_u32_e32 v105, vcc, 0, v93, vcc
	v_add_co_u32_e32 v106, vcc, 0x4c000, v92
	s_nop 1
	v_addc_co_u32_e32 v107, vcc, 0, v93, vcc
	v_add_co_u32_e32 v108, vcc, 0x50000, v92
	s_nop 1
	v_addc_co_u32_e32 v109, vcc, 0, v93, vcc
	v_add_co_u32_e32 v110, vcc, 0x54000, v92
	s_nop 1
	v_addc_co_u32_e32 v111, vcc, 0, v93, vcc
	v_add_co_u32_e32 v112, vcc, 0x58000, v92
	s_nop 1
	v_addc_co_u32_e32 v113, vcc, 0, v93, vcc
	v_add_co_u32_e32 v114, vcc, 0x5c000, v92
	s_nop 1
	v_addc_co_u32_e32 v115, vcc, 0, v93, vcc
	global_load_dword v131, v[100:101], off nt
	global_load_dword v132, v[102:103], off nt
	global_load_dword v133, v[104:105], off nt
	global_load_dword v134, v[106:107], off nt
	global_load_dword v135, v[108:109], off nt
	global_load_dword v136, v[110:111], off nt
	global_load_dword v137, v[112:113], off nt
	s_nop 0
	global_load_dword v114, v[114:115], off nt
	v_add_co_u32_e32 v100, vcc, 0x60000, v92
	s_nop 1
	v_addc_co_u32_e32 v101, vcc, 0, v93, vcc
	v_add_co_u32_e32 v102, vcc, 0x64000, v92
	s_nop 1
	v_addc_co_u32_e32 v103, vcc, 0, v93, vcc
	v_add_co_u32_e32 v104, vcc, 0x68000, v92
	s_nop 1
	v_addc_co_u32_e32 v105, vcc, 0, v93, vcc
	v_add_co_u32_e32 v106, vcc, 0x6c000, v92
	s_nop 1
	v_addc_co_u32_e32 v107, vcc, 0, v93, vcc
	v_add_co_u32_e32 v108, vcc, 0x70000, v92
	s_nop 1
	v_addc_co_u32_e32 v109, vcc, 0, v93, vcc
	v_add_co_u32_e32 v110, vcc, 0x74000, v92
	s_nop 1
	v_addc_co_u32_e32 v111, vcc, 0, v93, vcc
	v_add_co_u32_e32 v112, vcc, 0x78000, v92
	s_nop 1
	v_addc_co_u32_e32 v113, vcc, 0, v93, vcc
	v_add_co_u32_e32 v92, vcc, 0x7c000, v92
	s_nop 1
	v_addc_co_u32_e32 v93, vcc, 0, v93, vcc
	global_load_dword v100, v[100:101], off nt
	s_nop 0
	global_load_dword v101, v[102:103], off nt
	s_nop 0
	global_load_dword v102, v[104:105], off nt
	global_load_dword v103, v[106:107], off nt
	s_nop 0
	global_load_dword v104, v[108:109], off nt
	global_load_dword v105, v[110:111], off nt
	global_load_dword v106, v[112:113], off nt
	s_nop 0
	global_load_dword v92, v[92:93], off nt
	v_add_u32_e32 v93, 0x400, v95
	s_waitcnt vmcnt(30)
; #define LAS __attribute__((address_space(3)))
; #define LDS_WAIT() asm volatile("s_waitcnt lgkmcnt(0)" ::: "memory")
; #define LDS_WAIT() asm volatile("s_waitcnt lgkmcnt(0)" ::: "memory")
; __device__ __forceinline__ unsigned pk2(float lo, float hi) { f32x2_ v = {lo, hi}; return __builtin_bit_cast(unsigned, __builtin_convertvector(v, bf16x2_)); }
; __device__ __forceinline__ void p0_transpose_item(const float* W, int K, int N, bf16* WT, int k0, int n0, int dst_row0, LAS float* scr, int lane) {
;     ...
;     for (int i = 0; i < 32; ++i) { const int kk = 2 * i + (lane >> 5); scr[kk * 33 + (lane & 31)] = tv[i]; }
;     LDS_WAIT(); asm volatile("" ::: "memory");
;     const int c = lane & 7;
; #pragma unroll
;     for (int j = 0; j < 4; ++j) { const int n = (lane >> 3) + 8 * j; const LAS float* s = scr + (8 * c) * 33 + n;
;         v4u o; o.x = pk2(s[0 * 33], s[1 * 33]); o.y = pk2(s[2 * 33], s[3 * 33]); o.z = pk2(s[4 * 33], s[5 * 33]); o.w = pk2(s[6 * 33], s[7 * 33]);
;         *(v4u*)(WT + (size_t)(dst_row0 + n) * K + k0 + 8 * c) = o; }
;     LDS_WAIT(); asm volatile("" ::: "memory");
; }
	ds_write2_b32 v95, v99, v116 offset1:66
	s_waitcnt vmcnt(28)
	ds_write2_b32 v95, v117, v118 offset0:132 offset1:198
	s_waitcnt vmcnt(26)
	ds_write2_b32 v93, v119, v120 offset0:8 offset1:74
	s_waitcnt vmcnt(24)
	ds_write2_b32 v93, v121, v122 offset0:140 offset1:206
	v_add_u32_e32 v93, 0x800, v95
	s_waitcnt vmcnt(22)
	ds_write2_b32 v93, v123, v124 offset0:16 offset1:82
	s_waitcnt vmcnt(20)
	ds_write2_b32 v93, v125, v126 offset0:148 offset1:214
	v_add_u32_e32 v93, 0xc00, v95
	s_waitcnt vmcnt(18)
	ds_write2_b32 v93, v127, v128 offset0:24 offset1:90
	s_waitcnt vmcnt(16)
	ds_write2_b32 v93, v129, v130 offset0:156 offset1:222
	v_add_u32_e32 v93, 0x1000, v95
	s_waitcnt vmcnt(14)
	ds_write2_b32 v93, v131, v132 offset0:32 offset1:98
	s_waitcnt vmcnt(12)
	ds_write2_b32 v93, v133, v134 offset0:164 offset1:230
	v_add_u32_e32 v93, 0x1400, v95
	s_waitcnt vmcnt(10)
	ds_write2_b32 v93, v135, v136 offset0:40 offset1:106
	s_waitcnt vmcnt(8)
	ds_write2_b32 v93, v137, v114 offset0:172 offset1:238
	v_add_u32_e32 v93, 0x1800, v95
	s_waitcnt vmcnt(6)
	ds_write2_b32 v93, v100, v101 offset0:48 offset1:114
	s_waitcnt vmcnt(4)
	ds_write2_b32 v93, v102, v103 offset0:180 offset1:246
	v_add_u32_e32 v93, 0x1c00, v95
	s_waitcnt vmcnt(2)
	ds_write2_b32 v93, v104, v105 offset0:56 offset1:122
	s_waitcnt vmcnt(0)
	ds_write2_b32 v93, v106, v92 offset0:188 offset1:254
	s_waitcnt lgkmcnt(0)
	ds_read2_b32 v[92:93], v94 offset0:33 offset1:41
	ds_read2_b32 v[104:105], v94 offset1:8
	ds_read2_b32 v[106:107], v94 offset0:66 offset1:74
	ds_read2_b32 v[108:109], v94 offset0:99 offset1:107
	ds_read2_b32 v[110:111], v94 offset0:132 offset1:140
	ds_read2_b32 v[112:113], v94 offset0:165 offset1:173
	ds_read2_b32 v[114:115], v94 offset0:198 offset1:206
	ds_read2_b32 v[116:117], v94 offset0:231 offset1:239
	v_add_u32_e32 v120, s4, v5
	v_ashrrev_i32_e32 v121, 31, v120
	v_lshl_add_u64 v[118:119], s[2:3], 1, v[64:65]
	v_lshlrev_b64 v[120:121], 12, v[120:121]
	s_waitcnt lgkmcnt(6)
	v_cvt_pk_bf16_f32 v100, v104, v92
	s_waitcnt lgkmcnt(4)
	v_cvt_pk_bf16_f32 v101, v106, v108
	s_waitcnt lgkmcnt(2)
	v_cvt_pk_bf16_f32 v102, v110, v112
	s_waitcnt lgkmcnt(0)
	v_cvt_pk_bf16_f32 v103, v114, v116
	v_lshl_add_u64 v[120:121], v[118:119], 0, v[120:121]
	v_add_u32_e32 v92, s4, v96
	global_store_dwordx4 v[120:121], v[100:103], off
	s_nop 1
	v_cvt_pk_bf16_f32 v100, v105, v93
	v_ashrrev_i32_e32 v93, 31, v92
	v_cvt_pk_bf16_f32 v101, v107, v109
	v_cvt_pk_bf16_f32 v102, v111, v113
	v_cvt_pk_bf16_f32 v103, v115, v117
	v_lshlrev_b64 v[92:93], 12, v[92:93]
	ds_read2_b32 v[104:105], v94 offset0:49 offset1:57
	ds_read2_b32 v[106:107], v94 offset0:16 offset1:24
	ds_read2_b32 v[108:109], v94 offset0:82 offset1:90
	ds_read2_b32 v[110:111], v94 offset0:115 offset1:123
	ds_read2_b32 v[112:113], v94 offset0:148 offset1:156
	ds_read2_b32 v[114:115], v94 offset0:181 offset1:189
	ds_read2_b32 v[116:117], v94 offset0:214 offset1:222
	ds_read2_b32 v[120:121], v94 offset0:247 offset1:255
	v_lshl_add_u64 v[92:93], v[118:119], 0, v[92:93]
	global_store_dwordx4 v[92:93], v[100:103], off
	v_add_u32_e32 v92, s4, v97
	v_ashrrev_i32_e32 v93, 31, v92
	v_lshlrev_b64 v[92:93], 12, v[92:93]
	s_waitcnt lgkmcnt(6)
	v_cvt_pk_bf16_f32 v100, v106, v104
	s_waitcnt lgkmcnt(4)
	v_cvt_pk_bf16_f32 v101, v108, v110
	s_waitcnt lgkmcnt(2)
	v_cvt_pk_bf16_f32 v102, v112, v114
	s_waitcnt lgkmcnt(0)
	v_cvt_pk_bf16_f32 v103, v116, v120
	v_lshl_add_u64 v[92:93], v[118:119], 0, v[92:93]
	global_store_dwordx4 v[92:93], v[100:103], off
	v_add_u32_e32 v92, s4, v98
	v_ashrrev_i32_e32 v93, 31, v92
	v_lshlrev_b64 v[92:93], 12, v[92:93]
	v_cvt_pk_bf16_f32 v100, v107, v105
	v_cvt_pk_bf16_f32 v101, v109, v111
	v_cvt_pk_bf16_f32 v102, v113, v115
	v_cvt_pk_bf16_f32 v103, v117, v121
	v_lshl_add_u64 v[92:93], v[118:119], 0, v[92:93]
	global_store_dwordx4 v[92:93], v[100:103], off
	s_waitcnt lgkmcnt(0)

; #define LAS __attribute__((address_space(3)))
; __device__ __forceinline__ void p0_transpose_item(const float* W, int K, int N, bf16* WT, int k0, int n0, int dst_row0, LAS float* scr, int lane) {
;     const bool ok = (n0 + (lane & 31)) < N;
;     float tv[32];
; #pragma unroll
;     for (int i = 0; i < 32; ++i) { const int kk = 2 * i + (lane >> 5); tv[i] = ok ? W[(size_t)(k0 + kk) * N + n0 + (lane & 31)] : 0.f; }
; #pragma unroll
;     for (int i = 0; i < 32; ++i) { const int kk = 2 * i + (lane >> 5); scr[kk * 33 + (lane & 31)] = tv[i]; }
; __device__ __forceinline__ void p0_prologue(Frame& F, const Args& a) {
;     ...
;         if (r < I_SQ) { const int kb = r / 64, nb = r % 64; p0_transpose_item(a.in[21], DMODEL, DMODEL, Wt_out, 64 * kb, 32 * nb, 32 * nb, scr, F.lane); continue; } r -= I_SQ;
.LBB0_36:
	s_andn2_b64 vcc, exec, s[2:3]
	s_cbranch_vccnz .LBB0_38
	s_add_i32 s0, s16, 0xffffdf60
	s_and_b32 s2, s0, 0xffffffc0
	s_add_i32 s0, s10, 0xfffbec00
	s_and_b32 s4, s0, 0x7e0
	v_add_u32_e32 v92, s2, v0
	s_lshl_b32 s0, s4, 2
	v_ashrrev_i32_e32 v93, 31, v92
	v_lshl_add_u64 v[100:101], v[66:67], 0, s[0:1]
	v_lshlrev_b64 v[92:93], 13, v[92:93]
	v_lshl_add_u64 v[92:93], v[100:101], 0, v[92:93]
	v_add_co_u32_e32 v100, vcc, 0x4000, v92
	s_mov_b32 s3, s1
	s_nop 0
	v_addc_co_u32_e32 v101, vcc, 0, v93, vcc
	v_add_co_u32_e32 v102, vcc, 0x8000, v92
	s_nop 1
	v_addc_co_u32_e32 v103, vcc, 0, v93, vcc
	v_add_co_u32_e32 v104, vcc, 0xc000, v92
	s_nop 1
	v_addc_co_u32_e32 v105, vcc, 0, v93, vcc
	v_add_co_u32_e32 v106, vcc, 0x10000, v92
	s_nop 1
	v_addc_co_u32_e32 v107, vcc, 0, v93, vcc
	v_add_co_u32_e32 v108, vcc, 0x14000, v92
	s_nop 1
	v_addc_co_u32_e32 v109, vcc, 0, v93, vcc
	v_add_co_u32_e32 v110, vcc, 0x18000, v92
	s_nop 1
	v_addc_co_u32_e32 v111, vcc, 0, v93, vcc
	v_add_co_u32_e32 v112, vcc, 0x1c000, v92
	s_nop 1
	v_addc_co_u32_e32 v113, vcc, 0, v93, vcc
	global_load_dword v99, v[92:93], off nt
	global_load_dword v116, v[100:101], off nt
	global_load_dword v117, v[102:103], off nt
	global_load_dword v118, v[104:105], off nt
	global_load_dword v119, v[106:107], off nt
	global_load_dword v120, v[108:109], off nt
	global_load_dword v121, v[110:111], off nt
	global_load_dword v122, v[112:113], off nt
	v_add_co_u32_e32 v100, vcc, 0x20000, v92
	s_nop 1
	v_addc_co_u32_e32 v101, vcc, 0, v93, vcc
	v_add_co_u32_e32 v102, vcc, 0x24000, v92
	s_nop 1
	v_addc_co_u32_e32 v103, vcc, 0, v93, vcc
	v_add_co_u32_e32 v104, vcc, 0x28000, v92
	s_nop 1
	v_addc_co_u32_e32 v105, vcc, 0, v93, vcc
	v_add_co_u32_e32 v106, vcc, 0x2c000, v92
	s_nop 1
	v_addc_co_u32_e32 v107, vcc, 0, v93, vcc
	v_add_co_u32_e32 v108, vcc, 0x30000, v92
	s_nop 1
	v_addc_co_u32_e32 v109, vcc, 0, v93, vcc
	v_add_co_u32_e32 v110, vcc, 0x34000, v92
	s_nop 1
	v_addc_co_u32_e32 v111, vcc, 0, v93, vcc
	v_add_co_u32_e32 v112, vcc, 0x38000, v92
	s_nop 1
	v_addc_co_u32_e32 v113, vcc, 0, v93, vcc
	v_add_co_u32_e32 v114, vcc, 0x3c000, v92
	s_nop 1
	v_addc_co_u32_e32 v115, vcc, 0, v93, vcc
	global_load_dword v123, v[100:101], off nt
	global_load_dword v124, v[102:103], off nt
	global_load_dword v125, v[104:105], off nt
	global_load_dword v126, v[106:107], off nt
	global_load_dword v127, v[108:109], off nt
	global_load_dword v128, v[110:111], off nt
	global_load_dword v129, v[112:113], off nt
	global_load_dword v130, v[114:115], off nt
	v_add_co_u32_e32 v100, vcc, 0x40000, v92
	s_nop 1
	v_addc_co_u32_e32 v101, vcc, 0, v93, vcc
	v_add_co_u32_e32 v102, vcc, 0x44000, v92
	s_nop 1
	v_addc_co_u32_e32 v103, vcc, 0, v93, vcc
	v_add_co_u32_e32 v104, vcc, 0x48000, v92
	s_nop 1
	v_addc_co_u32_e32 v105, vcc, 0, v93, vcc
	v_add_co_u32_e32 v106, vcc, 0x4c000, v92
	s_nop 1
	v_addc_co_u32_e32 v107, vcc, 0, v93, vcc
	v_add_co_u32_e32 v108, vcc, 0x50000, v92
	s_nop 1
	v_addc_co_u32_e32 v109, vcc, 0, v93, vcc
	v_add_co_u32_e32 v110, vcc, 0x54000, v92
	s_nop 1
	v_addc_co_u32_e32 v111, vcc, 0, v93, vcc
	v_add_co_u32_e32 v112, vcc, 0x58000, v92
	s_nop 1
	v_addc_co_u32_e32 v113, vcc, 0, v93, vcc
	v_add_co_u32_e32 v114, vcc, 0x5c000, v92
	s_nop 1
	v_addc_co_u32_e32 v115, vcc, 0, v93, vcc
	global_load_dword v131, v[100:101], off nt
	global_load_dword v132, v[102:103], off nt
	global_load_dword v133, v[104:105], off nt
	global_load_dword v134, v[106:107], off nt
	global_load_dword v135, v[108:109], off nt
	global_load_dword v136, v[110:111], off nt
	global_load_dword v137, v[112:113], off nt
	s_nop 0
	global_load_dword v114, v[114:115], off nt
	v_add_co_u32_e32 v100, vcc, 0x60000, v92
	s_nop 1
	v_addc_co_u32_e32 v101, vcc, 0, v93, vcc
	v_add_co_u32_e32 v102, vcc, 0x64000, v92
	s_nop 1
	v_addc_co_u32_e32 v103, vcc, 0, v93, vcc
	v_add_co_u32_e32 v104, vcc, 0x68000, v92
	s_nop 1
	v_addc_co_u32_e32 v105, vcc, 0, v93, vcc
	v_add_co_u32_e32 v106, vcc, 0x6c000, v92
	s_nop 1
	v_addc_co_u32_e32 v107, vcc, 0, v93, vcc
	v_add_co_u32_e32 v108, vcc, 0x70000, v92
	s_nop 1
	v_addc_co_u32_e32 v109, vcc, 0, v93, vcc
	v_add_co_u32_e32 v110, vcc, 0x74000, v92
	s_nop 1
	v_addc_co_u32_e32 v111, vcc, 0, v93, vcc
	v_add_co_u32_e32 v112, vcc, 0x78000, v92
	s_nop 1
	v_addc_co_u32_e32 v113, vcc, 0, v93, vcc
	v_add_co_u32_e32 v92, vcc, 0x7c000, v92
	s_nop 1
	v_addc_co_u32_e32 v93, vcc, 0, v93, vcc
	global_load_dword v100, v[100:101], off nt
	s_nop 0
	global_load_dword v101, v[102:103], off nt
	s_nop 0
	global_load_dword v102, v[104:105], off nt
	global_load_dword v103, v[106:107], off nt
	s_nop 0
	global_load_dword v104, v[108:109], off nt
	global_load_dword v105, v[110:111], off nt
	global_load_dword v106, v[112:113], off nt
	s_nop 0
	global_load_dword v92, v[92:93], off nt
	v_add_u32_e32 v93, 0x400, v95
	s_waitcnt vmcnt(30)
; #define LAS __attribute__((address_space(3)))
; #define LDS_WAIT() asm volatile("s_waitcnt lgkmcnt(0)" ::: "memory")
; #define LDS_WAIT() asm volatile("s_waitcnt lgkmcnt(0)" ::: "memory")
; __device__ __forceinline__ unsigned pk2(float lo, float hi) { f32x2_ v = {lo, hi}; return __builtin_bit_cast(unsigned, __builtin_convertvector(v, bf16x2_)); }
; __device__ __forceinline__ void p0_transpose_item(const float* W, int K, int N, bf16* WT, int k0, int n0, int dst_row0, LAS float* scr, int lane) {
;     ...
;     for (int i = 0; i < 32; ++i) { const int kk = 2 * i + (lane >> 5); scr[kk * 33 + (lane & 31)] = tv[i]; }
;     LDS_WAIT(); asm volatile("" ::: "memory");
;     const int c = lane & 7;
; #pragma unroll
;     for (int j = 0; j < 4; ++j) { const int n = (lane >> 3) + 8 * j; const LAS float* s = scr + (8 * c) * 33 + n;
;         v4u o; o.x = pk2(s[0 * 33], s[1 * 33]); o.y = pk2(s[2 * 33], s[3 * 33]); o.z = pk2(s[4 * 33], s[5 * 33]); o.w = pk2(s[6 * 33], s[7 * 33]);
;         *(v4u*)(WT + (size_t)(dst_row0 + n) * K + k0 + 8 * c) = o; }
;     LDS_WAIT(); asm volatile("" ::: "memory");
; }
	ds_write2_b32 v95, v99, v116 offset1:66
	s_waitcnt vmcnt(28)
	ds_write2_b32 v95, v117, v118 offset0:132 offset1:198
	s_waitcnt vmcnt(26)
	ds_write2_b32 v93, v119, v120 offset0:8 offset1:74
	s_waitcnt vmcnt(24)
	ds_write2_b32 v93, v121, v122 offset0:140 offset1:206
	v_add_u32_e32 v93, 0x800, v95
	s_waitcnt vmcnt(22)
	ds_write2_b32 v93, v123, v124 offset0:16 offset1:82
	s_waitcnt vmcnt(20)
	ds_write2_b32 v93, v125, v126 offset0:148 offset1:214
	v_add_u32_e32 v93, 0xc00, v95
	s_waitcnt vmcnt(18)
	ds_write2_b32 v93, v127, v128 offset0:24 offset1:90
	s_waitcnt vmcnt(16)
	ds_write2_b32 v93, v129, v130 offset0:156 offset1:222
	v_add_u32_e32 v93, 0x1000, v95
	s_waitcnt vmcnt(14)
	ds_write2_b32 v93, v131, v132 offset0:32 offset1:98
	s_waitcnt vmcnt(12)
	ds_write2_b32 v93, v133, v134 offset0:164 offset1:230
	v_add_u32_e32 v93, 0x1400, v95
	s_waitcnt vmcnt(10)
	ds_write2_b32 v93, v135, v136 offset0:40 offset1:106
	s_waitcnt vmcnt(8)
	ds_write2_b32 v93, v137, v114 offset0:172 offset1:238
	v_add_u32_e32 v93, 0x1800, v95
	s_waitcnt vmcnt(6)
	ds_write2_b32 v93, v100, v101 offset0:48 offset1:114
	s_waitcnt vmcnt(4)
	ds_write2_b32 v93, v102, v103 offset0:180 offset1:246
	v_add_u32_e32 v93, 0x1c00, v95
	s_waitcnt vmcnt(2)
	ds_write2_b32 v93, v104, v105 offset0:56 offset1:122
	s_waitcnt vmcnt(0)
	ds_write2_b32 v93, v106, v92 offset0:188 offset1:254
	s_waitcnt lgkmcnt(0)
	ds_read2_b32 v[92:93], v94 offset0:33 offset1:41
	ds_read2_b32 v[104:105], v94 offset1:8
	ds_read2_b32 v[106:107], v94 offset0:66 offset1:74
	ds_read2_b32 v[108:109], v94 offset0:99 offset1:107
	ds_read2_b32 v[110:111], v94 offset0:132 offset1:140
	ds_read2_b32 v[112:113], v94 offset0:165 offset1:173
	ds_read2_b32 v[114:115], v94 offset0:198 offset1:206
	ds_read2_b32 v[116:117], v94 offset0:231 offset1:239
	v_add_u32_e32 v120, s4, v5
	v_ashrrev_i32_e32 v121, 31, v120
	v_lshl_add_u64 v[118:119], s[2:3], 1, v[70:71]
	v_lshlrev_b64 v[120:121], 12, v[120:121]
	s_waitcnt lgkmcnt(6)
	v_cvt_pk_bf16_f32 v100, v104, v92
	s_waitcnt lgkmcnt(4)
	v_cvt_pk_bf16_f32 v101, v106, v108
	s_waitcnt lgkmcnt(2)
	v_cvt_pk_bf16_f32 v102, v110, v112
	s_waitcnt lgkmcnt(0)
	v_cvt_pk_bf16_f32 v103, v114, v116
	v_lshl_add_u64 v[120:121], v[118:119], 0, v[120:121]
	v_add_u32_e32 v92, s4, v96
	global_store_dwordx4 v[120:121], v[100:103], off
	s_nop 1
	v_cvt_pk_bf16_f32 v100, v105, v93
	v_ashrrev_i32_e32 v93, 31, v92
	v_cvt_pk_bf16_f32 v101, v107, v109
	v_cvt_pk_bf16_f32 v102, v111, v113
	v_cvt_pk_bf16_f32 v103, v115, v117
	v_lshlrev_b64 v[92:93], 12, v[92:93]
	ds_read2_b32 v[104:105], v94 offset0:49 offset1:57
	ds_read2_b32 v[106:107], v94 offset0:16 offset1:24
	ds_read2_b32 v[108:109], v94 offset0:82 offset1:90
	ds_read2_b32 v[110:111], v94 offset0:115 offset1:123
	ds_read2_b32 v[112:113], v94 offset0:148 offset1:156
	ds_read2_b32 v[114:115], v94 offset0:181 offset1:189
	ds_read2_b32 v[116:117], v94 offset0:214 offset1:222
	ds_read2_b32 v[120:121], v94 offset0:247 offset1:255
	v_lshl_add_u64 v[92:93], v[118:119], 0, v[92:93]
	global_store_dwordx4 v[92:93], v[100:103], off
	v_add_u32_e32 v92, s4, v97
	v_ashrrev_i32_e32 v93, 31, v92
	v_lshlrev_b64 v[92:93], 12, v[92:93]
	s_waitcnt lgkmcnt(6)
	v_cvt_pk_bf16_f32 v100, v106, v104
	s_waitcnt lgkmcnt(4)
	v_cvt_pk_bf16_f32 v101, v108, v110
	s_waitcnt lgkmcnt(2)
	v_cvt_pk_bf16_f32 v102, v112, v114
	s_waitcnt lgkmcnt(0)
	v_cvt_pk_bf16_f32 v103, v116, v120
	v_lshl_add_u64 v[92:93], v[118:119], 0, v[92:93]
	global_store_dwordx4 v[92:93], v[100:103], off
	v_add_u32_e32 v92, s4, v98
	v_ashrrev_i32_e32 v93, 31, v92
	v_lshlrev_b64 v[92:93], 12, v[92:93]
	v_cvt_pk_bf16_f32 v100, v107, v105
	v_cvt_pk_bf16_f32 v101, v109, v111
	v_cvt_pk_bf16_f32 v102, v113, v115
	v_cvt_pk_bf16_f32 v103, v117, v121
	v_lshl_add_u64 v[92:93], v[118:119], 0, v[92:93]
	global_store_dwordx4 v[92:93], v[100:103], off
	s_waitcnt lgkmcnt(0)

; #define LAS __attribute__((address_space(3)))
; __device__ __forceinline__ void p0_transpose_item(const float* W, int K, int N, bf16* WT, int k0, int n0, int dst_row0, LAS float* scr, int lane) {
;     const bool ok = (n0 + (lane & 31)) < N;
;     float tv[32];
; #pragma unroll
;     for (int i = 0; i < 32; ++i) { const int kk = 2 * i + (lane >> 5); tv[i] = ok ? W[(size_t)(k0 + kk) * N + n0 + (lane & 31)] : 0.f; }
; __device__ __forceinline__ void p0_prologue(Frame& F, const Args& a) {
;     ...
;         if (r < I_IN) { const int kb = r / NB_IN, nb = r % NB_IN; p0_transpose_item(a.in[3], DMODEL, INCOLS, Wt_in, 64 * kb, 32 * nb, win_map(32 * nb), scr, F.lane); continue; } r -= I_IN;
.LBB0_54:
	s_lshl_b32 s4, s3, 6
	v_add_u32_e32 v92, s2, v1
	s_ashr_i32 s3, s2, 31
	v_cmp_gt_i32_e32 vcc, s14, v92
	v_add_u32_e32 v99, s4, v0
	v_lshl_add_u64 v[92:93], s[2:3], 2, v[68:69]
	v_mov_b32_e32 v101, 0
	v_mov_b32_e32 v100, 0
	s_and_saveexec_b64 s[2:3], vcc
	s_cbranch_execz .LBB0_56
	v_mad_i64_i32 v[102:103], s[18:19], v99, s15, v[92:93]
	global_load_dword v100, v[102:103], off nt
.LBB0_56:
	s_or_b64 exec, exec, s[2:3]
	s_and_saveexec_b64 s[2:3], vcc
	s_cbranch_execz .LBB0_58
	v_add_u32_e32 v101, 2, v99
	v_mad_i64_i32 v[102:103], s[18:19], v101, s15, v[92:93]
	global_load_dword v101, v[102:103], off nt
.LBB0_58:
	s_or_b64 exec, exec, s[2:3]
	v_mov_b32_e32 v102, 0
	v_mov_b32_e32 v103, 0
	s_and_saveexec_b64 s[2:3], vcc
	s_cbranch_execz .LBB0_60
	v_add_u32_e32 v103, 4, v99
	v_mad_i64_i32 v[104:105], s[18:19], v103, s15, v[92:93]
	global_load_dword v103, v[104:105], off nt
.LBB0_60:
	s_or_b64 exec, exec, s[2:3]
	s_and_saveexec_b64 s[2:3], vcc
	s_cbranch_execz .LBB0_62
	v_add_u32_e32 v102, 6, v99
	v_mad_i64_i32 v[104:105], s[18:19], v102, s15, v[92:93]
	global_load_dword v102, v[104:105], off nt
.LBB0_62:
	s_or_b64 exec, exec, s[2:3]
	v_mov_b32_e32 v104, 0
	v_mov_b32_e32 v105, 0
	s_and_saveexec_b64 s[2:3], vcc
	s_cbranch_execz .LBB0_64
	v_add_u32_e32 v105, 8, v99
	v_mad_i64_i32 v[106:107], s[18:19], v105, s15, v[92:93]
	global_load_dword v105, v[106:107], off nt
.LBB0_64:
	s_or_b64 exec, exec, s[2:3]
	s_and_saveexec_b64 s[2:3], vcc
	s_cbranch_execz .LBB0_66
	v_add_u32_e32 v104, 10, v99
	v_mad_i64_i32 v[106:107], s[18:19], v104, s15, v[92:93]
	global_load_dword v104, v[106:107], off nt
.LBB0_66:
	s_or_b64 exec, exec, s[2:3]
	v_mov_b32_e32 v106, 0
	v_mov_b32_e32 v107, 0
	s_and_saveexec_b64 s[2:3], vcc
	s_cbranch_execz .LBB0_68
	v_add_u32_e32 v107, 12, v99
	v_mad_i64_i32 v[108:109], s[18:19], v107, s15, v[92:93]
	global_load_dword v107, v[108:109], off nt
.LBB0_68:
	s_or_b64 exec, exec, s[2:3]
	s_and_saveexec_b64 s[2:3], vcc
	s_cbranch_execz .LBB0_70
	v_add_u32_e32 v106, 14, v99
	v_mad_i64_i32 v[108:109], s[18:19], v106, s15, v[92:93]
	global_load_dword v106, v[108:109], off nt
.LBB0_70:
	s_or_b64 exec, exec, s[2:3]
	v_mov_b32_e32 v108, 0
	v_mov_b32_e32 v109, 0
	s_and_saveexec_b64 s[2:3], vcc
	s_cbranch_execz .LBB0_72
	v_add_u32_e32 v109, 16, v99
	v_mad_i64_i32 v[110:111], s[18:19], v109, s15, v[92:93]
	global_load_dword v109, v[110:111], off nt
.LBB0_72:
	s_or_b64 exec, exec, s[2:3]
	s_and_saveexec_b64 s[2:3], vcc
	s_cbranch_execz .LBB0_74
	v_add_u32_e32 v108, 18, v99
	v_mad_i64_i32 v[110:111], s[18:19], v108, s15, v[92:93]
	global_load_dword v108, v[110:111], off nt
.LBB0_74:
	s_or_b64 exec, exec, s[2:3]
	v_mov_b32_e32 v110, 0
	v_mov_b32_e32 v111, 0
	s_and_saveexec_b64 s[2:3], vcc
	s_cbranch_execz .LBB0_76
	v_add_u32_e32 v111, 20, v99
	v_mad_i64_i32 v[112:113], s[18:19], v111, s15, v[92:93]
	global_load_dword v111, v[112:113], off nt
.LBB0_76:
	s_or_b64 exec, exec, s[2:3]
	s_and_saveexec_b64 s[2:3], vcc
	s_cbranch_execz .LBB0_78
	v_add_u32_e32 v110, 22, v99
	v_mad_i64_i32 v[112:113], s[18:19], v110, s15, v[92:93]
	global_load_dword v110, v[112:113], off nt
.LBB0_78:
	s_or_b64 exec, exec, s[2:3]
	v_mov_b32_e32 v112, 0
	v_mov_b32_e32 v113, 0
	s_and_saveexec_b64 s[2:3], vcc
	s_cbranch_execz .LBB0_80
	v_add_u32_e32 v113, 24, v99
	v_mad_i64_i32 v[114:115], s[18:19], v113, s15, v[92:93]
	global_load_dword v113, v[114:115], off nt
.LBB0_80:
	s_or_b64 exec, exec, s[2:3]
	s_and_saveexec_b64 s[2:3], vcc
	s_cbranch_execz .LBB0_82
	v_add_u32_e32 v112, 26, v99
	v_mad_i64_i32 v[114:115], s[18:19], v112, s15, v[92:93]
	global_load_dword v112, v[114:115], off nt
.LBB0_82:
	s_or_b64 exec, exec, s[2:3]
	v_mov_b32_e32 v114, 0
	v_mov_b32_e32 v115, 0
	s_and_saveexec_b64 s[2:3], vcc
	s_cbranch_execz .LBB0_84
	v_add_u32_e32 v115, 28, v99
	v_mad_i64_i32 v[116:117], s[18:19], v115, s15, v[92:93]
	global_load_dword v115, v[116:117], off nt
.LBB0_84:
	s_or_b64 exec, exec, s[2:3]
	s_and_saveexec_b64 s[2:3], vcc
	s_cbranch_execz .LBB0_86
	v_add_u32_e32 v114, 30, v99
	v_mad_i64_i32 v[116:117], s[18:19], v114, s15, v[92:93]
	global_load_dword v114, v[116:117], off nt
; __device__ __forceinline__ void p0_transpose_item(const float* W, int K, int N, bf16* WT, int k0, int n0, int dst_row0, LAS float* scr, int lane) {
;     const bool ok = (n0 + (lane & 31)) < N;
;     float tv[32];
; #pragma unroll
;     for (int i = 0; i < 32; ++i) { const int kk = 2 * i + (lane >> 5); tv[i] = ok ? W[(size_t)(k0 + kk) * N + n0 + (lane & 31)] : 0.f; }
.LBB0_86:
	s_or_b64 exec, exec, s[2:3]
	v_mov_b32_e32 v116, 0
	v_mov_b32_e32 v117, 0
	s_and_saveexec_b64 s[2:3], vcc
	s_cbranch_execz .LBB0_88
	v_add_u32_e32 v117, 32, v99
	v_mad_i64_i32 v[118:119], s[18:19], v117, s15, v[92:93]
	global_load_dword v117, v[118:119], off nt
.LBB0_88:
	s_or_b64 exec, exec, s[2:3]
	s_and_saveexec_b64 s[2:3], vcc
	s_cbranch_execz .LBB0_90
	v_add_u32_e32 v116, 34, v99
	v_mad_i64_i32 v[118:119], s[18:19], v116, s15, v[92:93]
	global_load_dword v116, v[118:119], off nt
.LBB0_90:
	s_or_b64 exec, exec, s[2:3]
	v_mov_b32_e32 v118, 0
	v_mov_b32_e32 v119, 0
	s_and_saveexec_b64 s[2:3], vcc
	s_cbranch_execz .LBB0_92
	v_add_u32_e32 v119, 36, v99
	v_mad_i64_i32 v[120:121], s[18:19], v119, s15, v[92:93]
	global_load_dword v119, v[120:121], off nt
.LBB0_92:
	s_or_b64 exec, exec, s[2:3]
	s_and_saveexec_b64 s[2:3], vcc
	s_cbranch_execz .LBB0_94
	v_add_u32_e32 v118, 38, v99
	v_mad_i64_i32 v[120:121], s[18:19], v118, s15, v[92:93]
	global_load_dword v118, v[120:121], off nt
.LBB0_94:
	s_or_b64 exec, exec, s[2:3]
	v_mov_b32_e32 v120, 0
	v_mov_b32_e32 v121, 0
	s_and_saveexec_b64 s[2:3], vcc
	s_cbranch_execz .LBB0_96
	v_add_u32_e32 v121, 40, v99
	v_mad_i64_i32 v[122:123], s[18:19], v121, s15, v[92:93]
	global_load_dword v121, v[122:123], off nt
.LBB0_96:
	s_or_b64 exec, exec, s[2:3]
	s_and_saveexec_b64 s[2:3], vcc
	s_cbranch_execz .LBB0_98
	v_add_u32_e32 v120, 42, v99
	v_mad_i64_i32 v[122:123], s[18:19], v120, s15, v[92:93]
	global_load_dword v120, v[122:123], off nt
.LBB0_98:
	s_or_b64 exec, exec, s[2:3]
	v_mov_b32_e32 v122, 0
	v_mov_b32_e32 v123, 0
	s_and_saveexec_b64 s[2:3], vcc
	s_cbranch_execz .LBB0_100
	v_add_u32_e32 v123, 44, v99
	v_mad_i64_i32 v[124:125], s[18:19], v123, s15, v[92:93]
	global_load_dword v123, v[124:125], off nt
.LBB0_100:
	s_or_b64 exec, exec, s[2:3]
	s_and_saveexec_b64 s[2:3], vcc
	s_cbranch_execz .LBB0_102
	v_add_u32_e32 v122, 46, v99
	v_mad_i64_i32 v[124:125], s[18:19], v122, s15, v[92:93]
	global_load_dword v122, v[124:125], off nt
.LBB0_102:
	s_or_b64 exec, exec, s[2:3]
	v_mov_b32_e32 v124, 0
	v_mov_b32_e32 v125, 0
	s_and_saveexec_b64 s[2:3], vcc
	s_cbranch_execz .LBB0_104
	v_add_u32_e32 v125, 48, v99
	v_mad_i64_i32 v[126:127], s[18:19], v125, s15, v[92:93]
	global_load_dword v125, v[126:127], off nt
.LBB0_104:
	s_or_b64 exec, exec, s[2:3]
	s_and_saveexec_b64 s[2:3], vcc
	s_cbranch_execz .LBB0_106
	v_add_u32_e32 v124, 50, v99
	v_mad_i64_i32 v[126:127], s[18:19], v124, s15, v[92:93]
	global_load_dword v124, v[126:127], off nt
.LBB0_106:
	s_or_b64 exec, exec, s[2:3]
	v_mov_b32_e32 v126, 0
	v_mov_b32_e32 v127, 0
	s_and_saveexec_b64 s[2:3], vcc
	s_cbranch_execz .LBB0_108
	v_add_u32_e32 v127, 52, v99
	v_mad_i64_i32 v[128:129], s[18:19], v127, s15, v[92:93]
	global_load_dword v127, v[128:129], off nt
.LBB0_108:
	s_or_b64 exec, exec, s[2:3]
	s_and_saveexec_b64 s[2:3], vcc
	s_cbranch_execz .LBB0_110
	v_add_u32_e32 v126, 54, v99
	v_mad_i64_i32 v[128:129], s[18:19], v126, s15, v[92:93]
	global_load_dword v126, v[128:129], off nt
.LBB0_110:
	s_or_b64 exec, exec, s[2:3]
	v_mov_b32_e32 v128, 0
	v_mov_b32_e32 v129, 0
	s_and_saveexec_b64 s[2:3], vcc
	s_cbranch_execz .LBB0_112
	v_add_u32_e32 v129, 56, v99
	v_mad_i64_i32 v[130:131], s[18:19], v129, s15, v[92:93]
	global_load_dword v129, v[130:131], off nt
.LBB0_112:
	s_or_b64 exec, exec, s[2:3]
	s_and_saveexec_b64 s[2:3], vcc
	s_cbranch_execz .LBB0_114
	v_add_u32_e32 v128, 58, v99
	v_mad_i64_i32 v[130:131], s[18:19], v128, s15, v[92:93]
	global_load_dword v128, v[130:131], off nt
.LBB0_114:
	s_or_b64 exec, exec, s[2:3]
	v_mov_b32_e32 v130, 0
	v_mov_b32_e32 v131, 0
	s_and_saveexec_b64 s[2:3], vcc
	s_cbranch_execz .LBB0_116
	v_add_u32_e32 v131, 60, v99
	v_mad_i64_i32 v[132:133], s[18:19], v131, s15, v[92:93]
	global_load_dword v131, v[132:133], off nt
.LBB0_116:
	s_or_b64 exec, exec, s[2:3]
	s_and_saveexec_b64 s[2:3], vcc
	s_cbranch_execz .LBB0_19
	v_add_u32_e32 v99, 62, v99
	v_mad_i64_i32 v[92:93], s[18:19], v99, s15, v[92:93]
	global_load_dword v130, v[92:93], off nt
	s_branch .LBB0_19
